# attention steps: 31-op med3 row-max trees -> 16-op max3 trees; sel-loop S1 init via srcC instead of 8 v_mov_b64
# speedup vs baseline: 1.0185x; 1.0044x over previous
.LBB0_106:
	s_and_b32 s4, s3, 0x4000
	s_add_i32 s45, s4, 0
	v_add_u32_e32 v50, s45, v133
	v_add_u32_e32 v51, v50, v134
	s_waitcnt vmcnt(1)
	ds_write_b128 v51, v[106:109] offset:49152
	v_add3_u32 v51, v50, v135, v136
	v_add3_u32 v50, v50, v137, v136
	s_waitcnt vmcnt(0)
	ds_write_b64 v51, v[102:103] offset:57344
	ds_write_b64 v50, v[104:105] offset:57344
	global_load_dwordx4 v[106:109], v[130:131], off
	global_load_dwordx4 v[102:105], v[128:129], off
	s_waitcnt lgkmcnt(3)
	v_lshrrev_b32_e32 v50, s33, v142
	v_and_b32_e32 v50, 1, v50
	v_cmp_eq_u32_e64 s[38:39], 1, v50
	v_bfe_u32 v50, v142, s33, 1
	s_andn2_b64 s[4:5], s[0:1], exec
	s_and_b64 s[40:41], s[0:1], exec
	v_cmp_ne_u32_e32 vcc, 0, v50
	s_or_b64 s[4:5], s[4:5], s[40:41]
	s_waitcnt lgkmcnt(0)
	s_barrier
	s_cbranch_vccz .LBB0_104
	v_add_u32_e32 v50, s45, v0
	s_mov_b32 s44, 0x7f800000
	v_add_u32_e32 v146, v50, v138
	ds_read_b128 v[66:69], v146 offset:49152
	v_add_u32_e32 v147, v50, v139
	ds_read_b128 v[110:113], v147 offset:49152
	v_add_u32_e32 v144, v50, v140
	ds_read_b128 v[114:117], v144 offset:49152
	v_add_u32_e32 v145, v50, v141
	ds_read_b128 v[118:121], v145 offset:49152
	ds_read_b128 v[122:125], v146 offset:53248
	ds_read_b128 v[148:151], v147 offset:53248
	ds_read_b128 v[152:155], v144 offset:53248
	ds_read_b128 v[156:159], v145 offset:53248
	s_waitcnt lgkmcnt(7)
	v_mfma_f32_32x32x16_bf16 v[50:65], v[66:69], v[98:101], v[34:49]
	s_waitcnt lgkmcnt(6)
	v_mfma_f32_32x32x16_bf16 v[50:65], v[110:113], v[86:89], v[50:65]
	s_cmp_lg_u64 vcc, -1
	s_cselect_b64 s[40:41], -1, 0
	s_cmp_eq_u64 vcc, -1
	s_cselect_b64 s[42:43], -1, 0
	s_or_b64 vcc, s[42:43], s[38:39]
	s_waitcnt lgkmcnt(3)
	v_mfma_f32_32x32x16_bf16 v[66:81], v[122:125], v[98:101], v[34:49]
	s_waitcnt lgkmcnt(2)
	v_mfma_f32_32x32x16_bf16 v[66:81], v[148:151], v[86:89], v[66:81]
	v_mfma_f32_32x32x16_bf16 v[50:65], v[114:117], v[82:85], v[50:65]
	s_waitcnt lgkmcnt(1)
	v_mfma_f32_32x32x16_bf16 v[66:81], v[152:155], v[82:85], v[66:81]
	v_mfma_f32_32x32x16_bf16 v[50:65], v[118:121], v[90:93], v[50:65]
	ds_read_b128 v[114:117], v146 offset:57344
	ds_read_b128 v[110:113], v147 offset:57344
	ds_read_b128 v[118:121], v144 offset:57344
	ds_read_b128 v[122:125], v145 offset:57344
	s_waitcnt lgkmcnt(4)
	v_mfma_f32_32x32x16_bf16 v[66:81], v[156:159], v[90:93], v[66:81]
	s_nop 5
	v_max3_f32 v149, v50, v51, v52
	v_max3_f32 v149, v149, v53, v54
	v_max3_f32 v149, v149, v55, v56
	v_max3_f32 v149, v149, v57, v58
	v_max3_f32 v149, v149, v59, v60
	v_max3_f32 v149, v149, v61, v62
	v_max3_f32 v149, v149, v63, v64
	v_max3_f32 v150, v66, v67, v68
	v_max3_f32 v150, v150, v69, v70
	v_max3_f32 v150, v150, v71, v72
	v_max3_f32 v150, v150, v73, v74
	v_max3_f32 v150, v150, v75, v76
	v_max3_f32 v150, v150, v77, v78
	v_max3_f32 v150, v150, v79, v80
	v_max3_f32 v148, v149, v150, v65
	v_max_f32_e32 v148, v148, v81
	v_cndmask_b32_e32 v148, v225, v148, vcc
	v_mov_b32_e32 v149, v148
	s_nop 1
	v_permlane32_swap_b32_e32 v148, v149
	v_max_f32_e32 v149, v149, v149
	v_max_f32_e32 v148, v148, v148
	v_max_f32_e32 v148, v148, v149
	v_cndmask_b32_e64 v149, v227, v228, s[0:1]
	v_cmp_gt_f32_e32 vcc, v148, v149
	s_cbranch_vccz .LBB0_109
	s_nop 0
	v_cndmask_b32_e32 v36, 0, v148, vcc
	v_exp_f32_e64 v38, -v36
	v_add_f32_e32 v143, v143, v36
	v_xor_b32_e32 v34, 0x80000000, v143
	v_pk_add_f32 v[50:51], v[50:51], v[36:37] op_sel_hi:[1,0] neg_lo:[0,1] neg_hi:[0,1]
	v_mul_f32_e32 v127, v127, v38
	v_pk_add_f32 v[66:67], v[66:67], v[36:37] op_sel_hi:[1,0] neg_lo:[0,1] neg_hi:[0,1]
	v_pk_add_f32 v[52:53], v[52:53], v[36:37] op_sel_hi:[1,0] neg_lo:[0,1] neg_hi:[0,1]
	v_pk_add_f32 v[68:69], v[68:69], v[36:37] op_sel_hi:[1,0] neg_lo:[0,1] neg_hi:[0,1]
	v_pk_add_f32 v[54:55], v[54:55], v[36:37] op_sel_hi:[1,0] neg_lo:[0,1] neg_hi:[0,1]
	v_pk_add_f32 v[70:71], v[70:71], v[36:37] op_sel_hi:[1,0] neg_lo:[0,1] neg_hi:[0,1]
	v_pk_add_f32 v[56:57], v[56:57], v[36:37] op_sel_hi:[1,0] neg_lo:[0,1] neg_hi:[0,1]
	v_pk_add_f32 v[72:73], v[72:73], v[36:37] op_sel_hi:[1,0] neg_lo:[0,1] neg_hi:[0,1]
	v_pk_add_f32 v[58:59], v[58:59], v[36:37] op_sel_hi:[1,0] neg_lo:[0,1] neg_hi:[0,1]
	v_pk_add_f32 v[74:75], v[74:75], v[36:37] op_sel_hi:[1,0] neg_lo:[0,1] neg_hi:[0,1]
	v_pk_add_f32 v[60:61], v[60:61], v[36:37] op_sel_hi:[1,0] neg_lo:[0,1] neg_hi:[0,1]
	v_pk_add_f32 v[76:77], v[76:77], v[36:37] op_sel_hi:[1,0] neg_lo:[0,1] neg_hi:[0,1]
	v_pk_add_f32 v[62:63], v[62:63], v[36:37] op_sel_hi:[1,0] neg_lo:[0,1] neg_hi:[0,1]
	v_pk_add_f32 v[78:79], v[78:79], v[36:37] op_sel_hi:[1,0] neg_lo:[0,1] neg_hi:[0,1]
	v_pk_mul_f32 v[16:17], v[16:17], v[38:39] op_sel_hi:[1,0]
	v_pk_mul_f32 v[14:15], v[14:15], v[38:39] op_sel_hi:[1,0]
	v_pk_mul_f32 v[12:13], v[12:13], v[38:39] op_sel_hi:[1,0]
	v_pk_mul_f32 v[10:11], v[10:11], v[38:39] op_sel_hi:[1,0]
	v_pk_mul_f32 v[8:9], v[8:9], v[38:39] op_sel_hi:[1,0]
	v_pk_mul_f32 v[6:7], v[6:7], v[38:39] op_sel_hi:[1,0]
	v_pk_mul_f32 v[4:5], v[4:5], v[38:39] op_sel_hi:[1,0]
	v_pk_mul_f32 v[2:3], v[2:3], v[38:39] op_sel_hi:[1,0]
	v_pk_mul_f32 v[32:33], v[32:33], v[38:39] op_sel_hi:[1,0]
	v_pk_mul_f32 v[30:31], v[30:31], v[38:39] op_sel_hi:[1,0]
	v_pk_mul_f32 v[28:29], v[28:29], v[38:39] op_sel_hi:[1,0]
	v_pk_mul_f32 v[26:27], v[26:27], v[38:39] op_sel_hi:[1,0]
	v_pk_mul_f32 v[24:25], v[24:25], v[38:39] op_sel_hi:[1,0]
	v_pk_mul_f32 v[22:23], v[22:23], v[38:39] op_sel_hi:[1,0]
	v_pk_mul_f32 v[20:21], v[20:21], v[38:39] op_sel_hi:[1,0]
	v_pk_mul_f32 v[18:19], v[18:19], v[38:39] op_sel_hi:[1,0]
	v_pk_add_f32 v[64:65], v[64:65], v[36:37] op_sel_hi:[1,0] neg_lo:[0,1] neg_hi:[0,1]
	v_pk_add_f32 v[80:81], v[80:81], v[36:37] op_sel_hi:[1,0] neg_lo:[0,1] neg_hi:[0,1]
	v_mov_b32_e32 v35, v34
	v_mov_b32_e32 v36, v34
	v_mov_b32_e32 v37, v34
	v_mov_b32_e32 v38, v34
	v_mov_b32_e32 v39, v34
	v_mov_b32_e32 v40, v34
	v_mov_b32_e32 v41, v34
	v_mov_b32_e32 v42, v34
	v_mov_b32_e32 v43, v34
	v_mov_b32_e32 v44, v34
	v_mov_b32_e32 v45, v34
	v_mov_b32_e32 v46, v34
	v_mov_b32_e32 v47, v34
	v_mov_b32_e32 v48, v34
	v_mov_b32_e32 v49, v34

.LBB0_129:
	s_nop 8
	v_max3_f32 v3, v34, v35, v36
	v_max3_f32 v3, v3, v37, v38
	v_max3_f32 v3, v3, v39, v40
	v_max3_f32 v3, v3, v41, v42
	v_max3_f32 v3, v3, v43, v44
	v_max3_f32 v3, v3, v45, v46
	v_max3_f32 v3, v3, v47, v48
	v_max3_f32 v4, v50, v51, v52
	v_max3_f32 v4, v4, v53, v54
	v_max3_f32 v4, v4, v55, v56
	v_max3_f32 v4, v4, v57, v58
	v_max3_f32 v4, v4, v59, v60
	v_max3_f32 v4, v4, v61, v62
	v_max3_f32 v4, v4, v63, v64
	v_max3_f32 v2, v3, v4, v49
	v_max_f32_e32 v2, v2, v65
	v_mov_b32_e32 v3, v2
	s_nop 1
	v_permlane32_swap_b32_e32 v2, v3
	v_max_f32_e32 v3, v3, v3
	v_max_f32_e32 v2, v2, v2
	v_max_f32_e32 v2, v2, v3
	v_cmp_lt_f32_e64 s[36:37], s24, v2
	s_mov_b64 vcc, s[36:37]
	s_cbranch_vccz .LBB0_139
	v_cndmask_b32_e64 v4, 0, v2, s[36:37]
	v_exp_f32_e64 v2, -v4
	v_add_f32_e32 v150, 0, v4
	v_xor_b32_e32 v18, 0x80000000, v150
	v_pk_add_f32 v[34:35], v[34:35], v[4:5] op_sel_hi:[1,0] neg_lo:[0,1] neg_hi:[0,1]
	v_mul_f32_e32 v2, 0, v2
	v_pk_add_f32 v[50:51], v[50:51], v[4:5] op_sel_hi:[1,0] neg_lo:[0,1] neg_hi:[0,1]
	v_pk_add_f32 v[36:37], v[36:37], v[4:5] op_sel_hi:[1,0] neg_lo:[0,1] neg_hi:[0,1]
	v_pk_add_f32 v[52:53], v[52:53], v[4:5] op_sel_hi:[1,0] neg_lo:[0,1] neg_hi:[0,1]
	v_pk_add_f32 v[38:39], v[38:39], v[4:5] op_sel_hi:[1,0] neg_lo:[0,1] neg_hi:[0,1]
	v_pk_add_f32 v[54:55], v[54:55], v[4:5] op_sel_hi:[1,0] neg_lo:[0,1] neg_hi:[0,1]
	v_pk_add_f32 v[40:41], v[40:41], v[4:5] op_sel_hi:[1,0] neg_lo:[0,1] neg_hi:[0,1]
	v_pk_add_f32 v[56:57], v[56:57], v[4:5] op_sel_hi:[1,0] neg_lo:[0,1] neg_hi:[0,1]
	v_pk_add_f32 v[42:43], v[42:43], v[4:5] op_sel_hi:[1,0] neg_lo:[0,1] neg_hi:[0,1]
	v_pk_add_f32 v[58:59], v[58:59], v[4:5] op_sel_hi:[1,0] neg_lo:[0,1] neg_hi:[0,1]
	v_pk_add_f32 v[44:45], v[44:45], v[4:5] op_sel_hi:[1,0] neg_lo:[0,1] neg_hi:[0,1]
	v_pk_add_f32 v[60:61], v[60:61], v[4:5] op_sel_hi:[1,0] neg_lo:[0,1] neg_hi:[0,1]
	v_pk_add_f32 v[46:47], v[46:47], v[4:5] op_sel_hi:[1,0] neg_lo:[0,1] neg_hi:[0,1]
	v_pk_add_f32 v[62:63], v[62:63], v[4:5] op_sel_hi:[1,0] neg_lo:[0,1] neg_hi:[0,1]
	v_pk_add_f32 v[48:49], v[48:49], v[4:5] op_sel_hi:[1,0] neg_lo:[0,1] neg_hi:[0,1]
	v_pk_add_f32 v[64:65], v[64:65], v[4:5] op_sel_hi:[1,0] neg_lo:[0,1] neg_hi:[0,1]
	v_mov_b32_e32 v19, v18
	v_mov_b32_e32 v20, v18
	v_mov_b32_e32 v21, v18
	v_mov_b32_e32 v22, v18
	v_mov_b32_e32 v23, v18
	v_mov_b32_e32 v24, v18
	v_mov_b32_e32 v25, v18
	v_mov_b32_e32 v26, v18
	v_mov_b32_e32 v27, v18
	v_mov_b32_e32 v28, v18
	v_mov_b32_e32 v29, v18
	v_mov_b32_e32 v30, v18
	v_mov_b32_e32 v31, v18
	v_mov_b32_e32 v32, v18
	v_mov_b32_e32 v33, v18
	s_branch .LBB0_140

.LBB0_137:
	s_nop 4
	v_max3_f32 v82, v50, v51, v52
	v_max3_f32 v82, v82, v53, v54
	v_max3_f32 v82, v82, v55, v56
	v_max3_f32 v82, v82, v57, v58
	v_max3_f32 v82, v82, v59, v60
	v_max3_f32 v82, v82, v61, v62
	v_max3_f32 v82, v82, v63, v64
	v_max3_f32 v83, v18, v19, v20
	v_max3_f32 v83, v83, v21, v22
	v_max3_f32 v83, v83, v23, v24
	v_max3_f32 v83, v83, v25, v26
	v_max3_f32 v83, v83, v27, v28
	v_max3_f32 v83, v83, v29, v30
	v_max3_f32 v83, v83, v31, v32
	v_max3_f32 v0, v82, v83, v65
	v_max_f32_e32 v0, v0, v33
	v_mov_b32_e32 v82, v0
	s_nop 1
	v_permlane32_swap_b32_e32 v0, v82
	v_max_f32_e32 v82, v82, v82
	v_max_f32_e32 v0, v0, v0
	v_max_f32_e32 v0, v0, v82
	v_cndmask_b32_e64 v82, v227, v228, s[18:19]
	v_cmp_gt_f32_e32 vcc, v0, v82
	s_cbranch_vccz .LBB0_60
	s_nop 0
	v_cndmask_b32_e32 v0, 0, v0, vcc
	v_exp_f32_e64 v82, -v0
	v_pk_add_f32 v[50:51], v[50:51], v[0:1] op_sel_hi:[1,0] neg_lo:[0,1] neg_hi:[0,1]
	v_pk_add_f32 v[18:19], v[18:19], v[0:1] op_sel_hi:[1,0] neg_lo:[0,1] neg_hi:[0,1]
	v_pk_add_f32 v[52:53], v[52:53], v[0:1] op_sel_hi:[1,0] neg_lo:[0,1] neg_hi:[0,1]
	v_mul_f32_e32 v149, v149, v82
	v_pk_add_f32 v[20:21], v[20:21], v[0:1] op_sel_hi:[1,0] neg_lo:[0,1] neg_hi:[0,1]
	v_pk_add_f32 v[54:55], v[54:55], v[0:1] op_sel_hi:[1,0] neg_lo:[0,1] neg_hi:[0,1]
	v_pk_add_f32 v[22:23], v[22:23], v[0:1] op_sel_hi:[1,0] neg_lo:[0,1] neg_hi:[0,1]
	v_pk_add_f32 v[56:57], v[56:57], v[0:1] op_sel_hi:[1,0] neg_lo:[0,1] neg_hi:[0,1]
	v_pk_add_f32 v[24:25], v[24:25], v[0:1] op_sel_hi:[1,0] neg_lo:[0,1] neg_hi:[0,1]
	v_pk_add_f32 v[58:59], v[58:59], v[0:1] op_sel_hi:[1,0] neg_lo:[0,1] neg_hi:[0,1]
	v_pk_add_f32 v[26:27], v[26:27], v[0:1] op_sel_hi:[1,0] neg_lo:[0,1] neg_hi:[0,1]
	v_pk_add_f32 v[60:61], v[60:61], v[0:1] op_sel_hi:[1,0] neg_lo:[0,1] neg_hi:[0,1]
	v_pk_add_f32 v[28:29], v[28:29], v[0:1] op_sel_hi:[1,0] neg_lo:[0,1] neg_hi:[0,1]
	v_pk_add_f32 v[62:63], v[62:63], v[0:1] op_sel_hi:[1,0] neg_lo:[0,1] neg_hi:[0,1]
	v_pk_add_f32 v[30:31], v[30:31], v[0:1] op_sel_hi:[1,0] neg_lo:[0,1] neg_hi:[0,1]
	v_pk_mul_f32 v[48:49], v[48:49], v[82:83] op_sel_hi:[1,0]
	v_pk_mul_f32 v[46:47], v[46:47], v[82:83] op_sel_hi:[1,0]
	v_pk_mul_f32 v[44:45], v[44:45], v[82:83] op_sel_hi:[1,0]
	v_pk_mul_f32 v[42:43], v[42:43], v[82:83] op_sel_hi:[1,0]
	v_pk_mul_f32 v[40:41], v[40:41], v[82:83] op_sel_hi:[1,0]
	v_pk_mul_f32 v[38:39], v[38:39], v[82:83] op_sel_hi:[1,0]
	v_pk_mul_f32 v[36:37], v[36:37], v[82:83] op_sel_hi:[1,0]
	v_pk_mul_f32 v[34:35], v[34:35], v[82:83] op_sel_hi:[1,0]
	v_pk_mul_f32 v[16:17], v[16:17], v[82:83] op_sel_hi:[1,0]
	v_pk_mul_f32 v[14:15], v[14:15], v[82:83] op_sel_hi:[1,0]
	v_pk_mul_f32 v[12:13], v[12:13], v[82:83] op_sel_hi:[1,0]
	v_pk_mul_f32 v[10:11], v[10:11], v[82:83] op_sel_hi:[1,0]
	v_pk_mul_f32 v[8:9], v[8:9], v[82:83] op_sel_hi:[1,0]
	v_pk_mul_f32 v[6:7], v[6:7], v[82:83] op_sel_hi:[1,0]
	v_pk_mul_f32 v[4:5], v[4:5], v[82:83] op_sel_hi:[1,0]
	v_pk_mul_f32 v[2:3], v[2:3], v[82:83] op_sel_hi:[1,0]
	v_pk_add_f32 v[64:65], v[64:65], v[0:1] op_sel_hi:[1,0] neg_lo:[0,1] neg_hi:[0,1]
	v_pk_add_f32 v[32:33], v[32:33], v[0:1] op_sel_hi:[1,0] neg_lo:[0,1] neg_hi:[0,1]
	s_branch .LBB0_60

.LBB0_143:
	s_and_b32 s6, s1, 0x4000
	s_add_i32 s18, s6, 0
	v_add_u32_e32 v50, s18, v133
	v_add_u32_e32 v51, v50, v134
	s_waitcnt vmcnt(1)
	ds_write_b128 v51, v[106:109] offset:49152
	v_add3_u32 v51, v50, v135, v136
	v_add3_u32 v50, v50, v137, v136
	s_waitcnt vmcnt(0)
	ds_write_b64 v51, v[102:103] offset:57344
	ds_write_b64 v50, v[104:105] offset:57344
	global_load_dwordx4 v[106:109], v[128:129], off
	global_load_dwordx4 v[102:105], v[126:127], off
	v_add_u32_e32 v54, s18, v0
	s_mov_b32 s6, 0x7f800000
	v_add_u32_e32 v154, v54, v138
	s_waitcnt lgkmcnt(0)
	s_barrier
	ds_read_b128 v[50:53], v154 offset:49152
	v_add_u32_e32 v153, v54, v139
	ds_read_b128 v[110:113], v153 offset:49152
	s_waitcnt lgkmcnt(1)
	v_mfma_f32_32x32x16_bf16 v[66:81], v[50:53], v[98:101], v[18:33]
	v_add_u32_e32 v152, v54, v140
	v_add_u32_e32 v151, v54, v141
	ds_read_b128 v[114:117], v152 offset:49152
	ds_read_b128 v[118:121], v151 offset:49152
	ds_read_b128 v[122:125], v154 offset:53248
	ds_read_b128 v[156:159], v153 offset:53248
	ds_read_b128 v[176:179], v152 offset:53248
	ds_read_b128 v[180:183], v151 offset:53248
	s_waitcnt lgkmcnt(3)
	v_mfma_f32_32x32x16_bf16 v[50:65], v[122:125], v[98:101], v[18:33]
	v_mfma_f32_32x32x16_bf16 v[66:81], v[110:113], v[86:89], v[66:81]
	s_waitcnt lgkmcnt(2)
	v_mfma_f32_32x32x16_bf16 v[50:65], v[156:159], v[86:89], v[50:65]
	v_mfma_f32_32x32x16_bf16 v[66:81], v[114:117], v[82:85], v[66:81]
	s_waitcnt lgkmcnt(1)
	v_mfma_f32_32x32x16_bf16 v[50:65], v[176:179], v[82:85], v[50:65]
	v_mfma_f32_32x32x16_bf16 v[66:81], v[118:121], v[90:93], v[66:81]
	ds_read_b128 v[114:117], v154 offset:57344
	ds_read_b128 v[110:113], v153 offset:57344
	ds_read_b128 v[118:121], v152 offset:57344
	ds_read_b128 v[122:125], v151 offset:57344
	s_waitcnt lgkmcnt(4)
	v_mfma_f32_32x32x16_bf16 v[50:65], v[180:183], v[90:93], v[50:65]
	s_nop 5
	v_max3_f32 v156, v66, v67, v68
	v_max3_f32 v156, v156, v69, v70
	v_max3_f32 v156, v156, v71, v72
	v_max3_f32 v156, v156, v73, v74
	v_max3_f32 v156, v156, v75, v76
	v_max3_f32 v156, v156, v77, v78
	v_max3_f32 v156, v156, v79, v80
	v_max3_f32 v157, v50, v51, v52
	v_max3_f32 v157, v157, v53, v54
	v_max3_f32 v157, v157, v55, v56
	v_max3_f32 v157, v157, v57, v58
	v_max3_f32 v157, v157, v59, v60
	v_max3_f32 v157, v157, v61, v62
	v_max3_f32 v157, v157, v63, v64
	v_max3_f32 v155, v156, v157, v81
	v_max_f32_e32 v155, v155, v65
	v_mov_b32_e32 v156, v155
	s_nop 1
	v_permlane32_swap_b32_e32 v155, v156
	v_max_f32_e32 v156, v156, v156
	v_max_f32_e32 v155, v155, v155
	v_max_f32_e32 v155, v155, v156
	v_cndmask_b32_e64 v156, v227, v228, s[36:37]
	v_cmp_gt_f32_e32 vcc, v155, v156
	s_cbranch_vccz .LBB0_142
	s_nop 0
	v_cndmask_b32_e32 v20, 0, v155, vcc
	v_exp_f32_e64 v22, -v20
	v_add_f32_e32 v150, v150, v20
	v_xor_b32_e32 v18, 0x80000000, v150
	v_pk_add_f32 v[66:67], v[66:67], v[20:21] op_sel_hi:[1,0] neg_lo:[0,1] neg_hi:[0,1]
	v_mul_f32_e32 v149, v149, v22
	v_pk_add_f32 v[50:51], v[50:51], v[20:21] op_sel_hi:[1,0] neg_lo:[0,1] neg_hi:[0,1]
	v_pk_add_f32 v[68:69], v[68:69], v[20:21] op_sel_hi:[1,0] neg_lo:[0,1] neg_hi:[0,1]
	v_pk_add_f32 v[52:53], v[52:53], v[20:21] op_sel_hi:[1,0] neg_lo:[0,1] neg_hi:[0,1]
	v_pk_add_f32 v[70:71], v[70:71], v[20:21] op_sel_hi:[1,0] neg_lo:[0,1] neg_hi:[0,1]
	v_pk_add_f32 v[54:55], v[54:55], v[20:21] op_sel_hi:[1,0] neg_lo:[0,1] neg_hi:[0,1]
	v_pk_add_f32 v[72:73], v[72:73], v[20:21] op_sel_hi:[1,0] neg_lo:[0,1] neg_hi:[0,1]
	v_pk_add_f32 v[56:57], v[56:57], v[20:21] op_sel_hi:[1,0] neg_lo:[0,1] neg_hi:[0,1]
	v_pk_add_f32 v[74:75], v[74:75], v[20:21] op_sel_hi:[1,0] neg_lo:[0,1] neg_hi:[0,1]
	v_pk_add_f32 v[58:59], v[58:59], v[20:21] op_sel_hi:[1,0] neg_lo:[0,1] neg_hi:[0,1]
	v_pk_add_f32 v[76:77], v[76:77], v[20:21] op_sel_hi:[1,0] neg_lo:[0,1] neg_hi:[0,1]
	v_pk_add_f32 v[60:61], v[60:61], v[20:21] op_sel_hi:[1,0] neg_lo:[0,1] neg_hi:[0,1]
	v_pk_add_f32 v[78:79], v[78:79], v[20:21] op_sel_hi:[1,0] neg_lo:[0,1] neg_hi:[0,1]
	v_pk_add_f32 v[62:63], v[62:63], v[20:21] op_sel_hi:[1,0] neg_lo:[0,1] neg_hi:[0,1]
	v_pk_mul_f32 v[48:49], v[48:49], v[22:23] op_sel_hi:[1,0]
	v_pk_mul_f32 v[46:47], v[46:47], v[22:23] op_sel_hi:[1,0]
	v_pk_mul_f32 v[44:45], v[44:45], v[22:23] op_sel_hi:[1,0]
	v_pk_mul_f32 v[42:43], v[42:43], v[22:23] op_sel_hi:[1,0]
	v_pk_mul_f32 v[40:41], v[40:41], v[22:23] op_sel_hi:[1,0]
	v_pk_mul_f32 v[38:39], v[38:39], v[22:23] op_sel_hi:[1,0]
	v_pk_mul_f32 v[36:37], v[36:37], v[22:23] op_sel_hi:[1,0]
	v_pk_mul_f32 v[34:35], v[34:35], v[22:23] op_sel_hi:[1,0]
	v_pk_mul_f32 v[16:17], v[16:17], v[22:23] op_sel_hi:[1,0]
	v_pk_mul_f32 v[14:15], v[14:15], v[22:23] op_sel_hi:[1,0]
	v_pk_mul_f32 v[12:13], v[12:13], v[22:23] op_sel_hi:[1,0]
	v_pk_mul_f32 v[10:11], v[10:11], v[22:23] op_sel_hi:[1,0]
	v_pk_mul_f32 v[8:9], v[8:9], v[22:23] op_sel_hi:[1,0]
	v_pk_mul_f32 v[6:7], v[6:7], v[22:23] op_sel_hi:[1,0]
	v_pk_mul_f32 v[4:5], v[4:5], v[22:23] op_sel_hi:[1,0]
	v_pk_mul_f32 v[2:3], v[2:3], v[22:23] op_sel_hi:[1,0]
	v_pk_add_f32 v[80:81], v[80:81], v[20:21] op_sel_hi:[1,0] neg_lo:[0,1] neg_hi:[0,1]
	v_pk_add_f32 v[64:65], v[64:65], v[20:21] op_sel_hi:[1,0] neg_lo:[0,1] neg_hi:[0,1]
	v_mov_b32_e32 v19, v18
	v_mov_b32_e32 v20, v18
	v_mov_b32_e32 v21, v18
	v_mov_b32_e32 v22, v18
	v_mov_b32_e32 v23, v18
	v_mov_b32_e32 v24, v18
	v_mov_b32_e32 v25, v18
	v_mov_b32_e32 v26, v18
	v_mov_b32_e32 v27, v18
	v_mov_b32_e32 v28, v18
	v_mov_b32_e32 v29, v18
	v_mov_b32_e32 v30, v18
	v_mov_b32_e32 v31, v18
	v_mov_b32_e32 v32, v18
	v_mov_b32_e32 v33, v18
	s_branch .LBB0_142

.LBB0_362:
	s_and_b32 s0, s43, 0x4000
	s_add_i32 s46, s0, 0
	v_add_u32_e32 v2, s46, v151
	v_add_u32_e32 v3, v2, v155
	s_waitcnt vmcnt(0)
	ds_write_b128 v3, v[114:117] offset:49152
	v_add3_u32 v3, v2, v153, v152
	v_add3_u32 v2, v2, v154, v152
	ds_write_b64 v3, v[118:119] offset:57344
	ds_write_b64 v2, v[120:121] offset:57344
	global_load_dwordx4 v[114:117], v[134:135], off
	global_load_dwordx4 v[118:121], v[132:133], off
	s_lshr_b32 s0, s44, 2
	v_lshrrev_b32_e32 v2, s0, v144
	v_and_b32_e32 v2, 1, v2
	v_cmp_eq_u32_e64 s[36:37], 1, v2
	v_bfe_u32 v2, v144, s0, 1
	s_andn2_b64 s[0:1], s[30:31], exec
	s_and_b64 s[38:39], s[30:31], exec
	v_cmp_ne_u32_e32 vcc, 0, v2
	s_or_b64 s[0:1], s[0:1], s[38:39]
	s_waitcnt lgkmcnt(0)
	s_barrier
	s_cbranch_vccz .LBB0_360
	v_add_u32_e32 v15, s46, v136
	s_mov_b32 s45, 0x7f800000
	v_add_u32_e32 v145, v15, v138
	ds_read_b128 v[2:5], v145 offset:49152
	v_add_u32_e32 v146, v15, v139
	ds_read_b128 v[6:9], v146 offset:49152
	v_add_u32_e32 v14, v15, v137
	ds_read_b128 v[10:13], v14 offset:49152
	v_add_u32_e32 v15, v15, v140
	ds_read_b128 v[122:125], v15 offset:49152
	ds_read_b128 v[156:159], v145 offset:53248
	ds_read_b128 v[160:163], v146 offset:53248
	ds_read_b128 v[164:167], v14 offset:53248
	ds_read_b128 v[168:171], v15 offset:53248
	s_waitcnt lgkmcnt(7)
	v_mfma_f32_32x32x16_bf16 v[64:79], v[2:5], v[110:113], v[48:63]
	s_cmp_lg_u64 vcc, -1
	s_cselect_b64 s[38:39], -1, 0
	s_cmp_eq_u64 vcc, -1
	s_cselect_b64 s[40:41], -1, 0
	s_or_b64 vcc, s[40:41], s[36:37]
	s_waitcnt lgkmcnt(3)
	v_mfma_f32_32x32x16_bf16 v[80:95], v[156:159], v[110:113], v[48:63]
	v_mfma_f32_32x32x16_bf16 v[64:79], v[6:9], v[106:109], v[64:79]
	s_waitcnt lgkmcnt(2)
	v_mfma_f32_32x32x16_bf16 v[80:95], v[160:163], v[106:109], v[80:95]
	v_mfma_f32_32x32x16_bf16 v[64:79], v[10:13], v[102:105], v[64:79]
	s_waitcnt lgkmcnt(1)
	v_mfma_f32_32x32x16_bf16 v[80:95], v[164:167], v[102:105], v[80:95]
	v_mfma_f32_32x32x16_bf16 v[64:79], v[122:125], v[98:101], v[64:79]
	ds_read_b128 v[6:9], v145 offset:57344
	ds_read_b128 v[2:5], v146 offset:57344
	ds_read_b128 v[10:13], v14 offset:57344
	ds_read_b128 v[122:125], v15 offset:57344
	s_waitcnt lgkmcnt(4)
	v_mfma_f32_32x32x16_bf16 v[80:95], v[168:171], v[98:101], v[80:95]
	s_nop 5
	v_max3_f32 v148, v64, v65, v66
	v_max3_f32 v148, v148, v67, v68
	v_max3_f32 v148, v148, v69, v70
	v_max3_f32 v148, v148, v71, v72
	v_max3_f32 v148, v148, v73, v74
	v_max3_f32 v148, v148, v75, v76
	v_max3_f32 v148, v148, v77, v78
	v_max3_f32 v149, v80, v81, v82
	v_max3_f32 v149, v149, v83, v84
	v_max3_f32 v149, v149, v85, v86
	v_max3_f32 v149, v149, v87, v88
	v_max3_f32 v149, v149, v89, v90
	v_max3_f32 v149, v149, v91, v92
	v_max3_f32 v149, v149, v93, v94
	v_max3_f32 v147, v148, v149, v79
	v_max_f32_e32 v147, v147, v95
	v_cndmask_b32_e32 v147, v225, v147, vcc
	v_mov_b32_e32 v148, v147
	s_nop 1
	v_permlane32_swap_b32_e32 v147, v148
	v_max_f32_e32 v148, v148, v148
	v_max_f32_e32 v147, v147, v147
	v_max_f32_e32 v147, v147, v148
	v_cndmask_b32_e64 v148, v227, v228, s[30:31]
	v_cmp_gt_f32_e32 vcc, v147, v148
	s_cbranch_vccz .LBB0_365
	s_nop 0
	v_cndmask_b32_e32 v50, 0, v147, vcc
	v_exp_f32_e64 v52, -v50
	v_add_f32_e32 v143, v143, v50
	v_xor_b32_e32 v48, 0x80000000, v143
	v_pk_add_f32 v[64:65], v[64:65], v[50:51] op_sel_hi:[1,0] neg_lo:[0,1] neg_hi:[0,1]
	v_mul_f32_e32 v0, v0, v52
	v_pk_add_f32 v[80:81], v[80:81], v[50:51] op_sel_hi:[1,0] neg_lo:[0,1] neg_hi:[0,1]
	v_pk_add_f32 v[66:67], v[66:67], v[50:51] op_sel_hi:[1,0] neg_lo:[0,1] neg_hi:[0,1]
	v_pk_add_f32 v[82:83], v[82:83], v[50:51] op_sel_hi:[1,0] neg_lo:[0,1] neg_hi:[0,1]
	v_pk_add_f32 v[68:69], v[68:69], v[50:51] op_sel_hi:[1,0] neg_lo:[0,1] neg_hi:[0,1]
	v_pk_add_f32 v[84:85], v[84:85], v[50:51] op_sel_hi:[1,0] neg_lo:[0,1] neg_hi:[0,1]
	v_pk_add_f32 v[70:71], v[70:71], v[50:51] op_sel_hi:[1,0] neg_lo:[0,1] neg_hi:[0,1]
	v_pk_add_f32 v[86:87], v[86:87], v[50:51] op_sel_hi:[1,0] neg_lo:[0,1] neg_hi:[0,1]
	v_pk_add_f32 v[72:73], v[72:73], v[50:51] op_sel_hi:[1,0] neg_lo:[0,1] neg_hi:[0,1]
	v_pk_add_f32 v[88:89], v[88:89], v[50:51] op_sel_hi:[1,0] neg_lo:[0,1] neg_hi:[0,1]
	v_pk_add_f32 v[74:75], v[74:75], v[50:51] op_sel_hi:[1,0] neg_lo:[0,1] neg_hi:[0,1]
	v_pk_add_f32 v[90:91], v[90:91], v[50:51] op_sel_hi:[1,0] neg_lo:[0,1] neg_hi:[0,1]
	v_pk_add_f32 v[76:77], v[76:77], v[50:51] op_sel_hi:[1,0] neg_lo:[0,1] neg_hi:[0,1]
	v_pk_add_f32 v[92:93], v[92:93], v[50:51] op_sel_hi:[1,0] neg_lo:[0,1] neg_hi:[0,1]
	v_pk_mul_f32 v[46:47], v[46:47], v[52:53] op_sel_hi:[1,0]
	v_pk_mul_f32 v[44:45], v[44:45], v[52:53] op_sel_hi:[1,0]
	v_pk_mul_f32 v[42:43], v[42:43], v[52:53] op_sel_hi:[1,0]
	v_pk_mul_f32 v[40:41], v[40:41], v[52:53] op_sel_hi:[1,0]
	v_pk_mul_f32 v[38:39], v[38:39], v[52:53] op_sel_hi:[1,0]
	v_pk_mul_f32 v[36:37], v[36:37], v[52:53] op_sel_hi:[1,0]
	v_pk_mul_f32 v[34:35], v[34:35], v[52:53] op_sel_hi:[1,0]
	v_pk_mul_f32 v[32:33], v[32:33], v[52:53] op_sel_hi:[1,0]
	v_pk_mul_f32 v[30:31], v[30:31], v[52:53] op_sel_hi:[1,0]
	v_pk_mul_f32 v[28:29], v[28:29], v[52:53] op_sel_hi:[1,0]
	v_pk_mul_f32 v[26:27], v[26:27], v[52:53] op_sel_hi:[1,0]
	v_pk_mul_f32 v[24:25], v[24:25], v[52:53] op_sel_hi:[1,0]
	v_pk_mul_f32 v[22:23], v[22:23], v[52:53] op_sel_hi:[1,0]
	v_pk_mul_f32 v[20:21], v[20:21], v[52:53] op_sel_hi:[1,0]
	v_pk_mul_f32 v[18:19], v[18:19], v[52:53] op_sel_hi:[1,0]
	v_pk_mul_f32 v[16:17], v[16:17], v[52:53] op_sel_hi:[1,0]
	v_pk_add_f32 v[78:79], v[78:79], v[50:51] op_sel_hi:[1,0] neg_lo:[0,1] neg_hi:[0,1]
	v_pk_add_f32 v[94:95], v[94:95], v[50:51] op_sel_hi:[1,0] neg_lo:[0,1] neg_hi:[0,1]
	v_mov_b32_e32 v49, v48
	v_mov_b32_e32 v50, v48
	v_mov_b32_e32 v51, v48
	v_mov_b32_e32 v52, v48
	v_mov_b32_e32 v53, v48
	v_mov_b32_e32 v54, v48
	v_mov_b32_e32 v55, v48
	v_mov_b32_e32 v56, v48
	v_mov_b32_e32 v57, v48
	v_mov_b32_e32 v58, v48
	v_mov_b32_e32 v59, v48
	v_mov_b32_e32 v60, v48
	v_mov_b32_e32 v61, v48
	v_mov_b32_e32 v62, v48
	v_mov_b32_e32 v63, v48

.LBB0_372:
	s_nop 7
	v_max3_f32 v164, v80, v81, v82
	v_max3_f32 v164, v164, v83, v84
	v_max3_f32 v164, v164, v85, v86
	v_max3_f32 v164, v164, v87, v88
	v_max3_f32 v164, v164, v89, v90
	v_max3_f32 v164, v164, v91, v92
	v_max3_f32 v164, v164, v93, v94
	v_max3_f32 v165, v64, v65, v66
	v_max3_f32 v165, v165, v67, v68
	v_max3_f32 v165, v165, v69, v70
	v_max3_f32 v165, v165, v71, v72
	v_max3_f32 v165, v165, v73, v74
	v_max3_f32 v165, v165, v75, v76
	v_max3_f32 v165, v165, v77, v78
	v_max3_f32 v163, v164, v165, v95
	v_max_f32_e32 v163, v163, v79
	v_mov_b32_e32 v164, v163
	s_nop 1
	v_permlane32_swap_b32_e32 v163, v164
	v_max_f32_e32 v164, v164, v164
	v_max_f32_e32 v163, v163, v163
	v_max_f32_e32 v163, v163, v164
	v_cndmask_b32_e64 v164, v227, v228, s[30:31]
	v_cmp_gt_f32_e32 vcc, v163, v164
	s_cbranch_vccz .LBB0_374
	s_nop 0
	v_cndmask_b32_e32 v50, 0, v163, vcc
	v_exp_f32_e64 v52, -v50
	v_add_f32_e32 v143, v143, v50
	v_xor_b32_e32 v48, 0x80000000, v143
	v_pk_add_f32 v[80:81], v[80:81], v[50:51] op_sel_hi:[1,0] neg_lo:[0,1] neg_hi:[0,1]
	v_mul_f32_e32 v0, v0, v52
	v_pk_add_f32 v[64:65], v[64:65], v[50:51] op_sel_hi:[1,0] neg_lo:[0,1] neg_hi:[0,1]
	v_pk_add_f32 v[82:83], v[82:83], v[50:51] op_sel_hi:[1,0] neg_lo:[0,1] neg_hi:[0,1]
	v_pk_add_f32 v[66:67], v[66:67], v[50:51] op_sel_hi:[1,0] neg_lo:[0,1] neg_hi:[0,1]
	v_pk_add_f32 v[84:85], v[84:85], v[50:51] op_sel_hi:[1,0] neg_lo:[0,1] neg_hi:[0,1]
	v_pk_add_f32 v[68:69], v[68:69], v[50:51] op_sel_hi:[1,0] neg_lo:[0,1] neg_hi:[0,1]
	v_pk_add_f32 v[86:87], v[86:87], v[50:51] op_sel_hi:[1,0] neg_lo:[0,1] neg_hi:[0,1]
	v_pk_add_f32 v[70:71], v[70:71], v[50:51] op_sel_hi:[1,0] neg_lo:[0,1] neg_hi:[0,1]
	v_pk_add_f32 v[88:89], v[88:89], v[50:51] op_sel_hi:[1,0] neg_lo:[0,1] neg_hi:[0,1]
	v_pk_add_f32 v[72:73], v[72:73], v[50:51] op_sel_hi:[1,0] neg_lo:[0,1] neg_hi:[0,1]
	v_pk_add_f32 v[90:91], v[90:91], v[50:51] op_sel_hi:[1,0] neg_lo:[0,1] neg_hi:[0,1]
	v_pk_add_f32 v[74:75], v[74:75], v[50:51] op_sel_hi:[1,0] neg_lo:[0,1] neg_hi:[0,1]
	v_pk_add_f32 v[92:93], v[92:93], v[50:51] op_sel_hi:[1,0] neg_lo:[0,1] neg_hi:[0,1]
	v_pk_add_f32 v[76:77], v[76:77], v[50:51] op_sel_hi:[1,0] neg_lo:[0,1] neg_hi:[0,1]
	v_pk_mul_f32 v[46:47], v[46:47], v[52:53] op_sel_hi:[1,0]
	v_pk_mul_f32 v[44:45], v[44:45], v[52:53] op_sel_hi:[1,0]
	v_pk_mul_f32 v[42:43], v[42:43], v[52:53] op_sel_hi:[1,0]
	v_pk_mul_f32 v[40:41], v[40:41], v[52:53] op_sel_hi:[1,0]
	v_pk_mul_f32 v[38:39], v[38:39], v[52:53] op_sel_hi:[1,0]
	v_pk_mul_f32 v[36:37], v[36:37], v[52:53] op_sel_hi:[1,0]
	v_pk_mul_f32 v[34:35], v[34:35], v[52:53] op_sel_hi:[1,0]
	v_pk_mul_f32 v[32:33], v[32:33], v[52:53] op_sel_hi:[1,0]
	v_pk_mul_f32 v[30:31], v[30:31], v[52:53] op_sel_hi:[1,0]
	v_pk_mul_f32 v[28:29], v[28:29], v[52:53] op_sel_hi:[1,0]
	v_pk_mul_f32 v[26:27], v[26:27], v[52:53] op_sel_hi:[1,0]
	v_pk_mul_f32 v[24:25], v[24:25], v[52:53] op_sel_hi:[1,0]
	v_pk_mul_f32 v[22:23], v[22:23], v[52:53] op_sel_hi:[1,0]
	v_pk_mul_f32 v[20:21], v[20:21], v[52:53] op_sel_hi:[1,0]
	v_pk_mul_f32 v[18:19], v[18:19], v[52:53] op_sel_hi:[1,0]
	v_pk_mul_f32 v[16:17], v[16:17], v[52:53] op_sel_hi:[1,0]
	v_pk_add_f32 v[94:95], v[94:95], v[50:51] op_sel_hi:[1,0] neg_lo:[0,1] neg_hi:[0,1]
	v_pk_add_f32 v[78:79], v[78:79], v[50:51] op_sel_hi:[1,0] neg_lo:[0,1] neg_hi:[0,1]
	v_mov_b32_e32 v49, v48
	v_mov_b32_e32 v50, v48
	v_mov_b32_e32 v51, v48
	v_mov_b32_e32 v52, v48
	v_mov_b32_e32 v53, v48
	v_mov_b32_e32 v54, v48
	v_mov_b32_e32 v55, v48
	v_mov_b32_e32 v56, v48
	v_mov_b32_e32 v57, v48
	v_mov_b32_e32 v58, v48
	v_mov_b32_e32 v59, v48
	v_mov_b32_e32 v60, v48
	v_mov_b32_e32 v61, v48
	v_mov_b32_e32 v62, v48
	v_mov_b32_e32 v63, v48

.LBB0_378:
	s_nop 7
	v_max3_f32 v162, v80, v81, v82
	v_max3_f32 v162, v162, v83, v84
	v_max3_f32 v162, v162, v85, v86
	v_max3_f32 v162, v162, v87, v88
	v_max3_f32 v162, v162, v89, v90
	v_max3_f32 v162, v162, v91, v92
	v_max3_f32 v162, v162, v93, v94
	v_max3_f32 v163, v64, v65, v66
	v_max3_f32 v163, v163, v67, v68
	v_max3_f32 v163, v163, v69, v70
	v_max3_f32 v163, v163, v71, v72
	v_max3_f32 v163, v163, v73, v74
	v_max3_f32 v163, v163, v75, v76
	v_max3_f32 v163, v163, v77, v78
	v_max3_f32 v161, v162, v163, v95
	v_max_f32_e32 v161, v161, v79
	v_mov_b32_e32 v162, v161
	s_nop 1
	v_permlane32_swap_b32_e32 v161, v162
	v_max_f32_e32 v162, v162, v162
	v_max_f32_e32 v161, v161, v161
	v_max_f32_e32 v161, v161, v162
	v_cndmask_b32_e64 v162, v227, v228, s[30:31]
	v_cmp_gt_f32_e32 vcc, v161, v162
	s_cbranch_vccz .LBB0_380
	s_nop 0
	v_cndmask_b32_e32 v50, 0, v161, vcc
	v_exp_f32_e64 v52, -v50
	v_add_f32_e32 v143, v143, v50
	v_xor_b32_e32 v48, 0x80000000, v143
	v_pk_add_f32 v[80:81], v[80:81], v[50:51] op_sel_hi:[1,0] neg_lo:[0,1] neg_hi:[0,1]
	v_mul_f32_e32 v0, v0, v52
	v_pk_add_f32 v[64:65], v[64:65], v[50:51] op_sel_hi:[1,0] neg_lo:[0,1] neg_hi:[0,1]
	v_pk_add_f32 v[82:83], v[82:83], v[50:51] op_sel_hi:[1,0] neg_lo:[0,1] neg_hi:[0,1]
	v_pk_add_f32 v[66:67], v[66:67], v[50:51] op_sel_hi:[1,0] neg_lo:[0,1] neg_hi:[0,1]
	v_pk_add_f32 v[84:85], v[84:85], v[50:51] op_sel_hi:[1,0] neg_lo:[0,1] neg_hi:[0,1]
	v_pk_add_f32 v[68:69], v[68:69], v[50:51] op_sel_hi:[1,0] neg_lo:[0,1] neg_hi:[0,1]
	v_pk_add_f32 v[86:87], v[86:87], v[50:51] op_sel_hi:[1,0] neg_lo:[0,1] neg_hi:[0,1]
	v_pk_add_f32 v[70:71], v[70:71], v[50:51] op_sel_hi:[1,0] neg_lo:[0,1] neg_hi:[0,1]
	v_pk_add_f32 v[88:89], v[88:89], v[50:51] op_sel_hi:[1,0] neg_lo:[0,1] neg_hi:[0,1]
	v_pk_add_f32 v[72:73], v[72:73], v[50:51] op_sel_hi:[1,0] neg_lo:[0,1] neg_hi:[0,1]
	v_pk_add_f32 v[90:91], v[90:91], v[50:51] op_sel_hi:[1,0] neg_lo:[0,1] neg_hi:[0,1]
	v_pk_add_f32 v[74:75], v[74:75], v[50:51] op_sel_hi:[1,0] neg_lo:[0,1] neg_hi:[0,1]
	v_pk_add_f32 v[92:93], v[92:93], v[50:51] op_sel_hi:[1,0] neg_lo:[0,1] neg_hi:[0,1]
	v_pk_add_f32 v[76:77], v[76:77], v[50:51] op_sel_hi:[1,0] neg_lo:[0,1] neg_hi:[0,1]
	v_pk_mul_f32 v[46:47], v[46:47], v[52:53] op_sel_hi:[1,0]
	v_pk_mul_f32 v[44:45], v[44:45], v[52:53] op_sel_hi:[1,0]
	v_pk_mul_f32 v[42:43], v[42:43], v[52:53] op_sel_hi:[1,0]
	v_pk_mul_f32 v[40:41], v[40:41], v[52:53] op_sel_hi:[1,0]
	v_pk_mul_f32 v[38:39], v[38:39], v[52:53] op_sel_hi:[1,0]
	v_pk_mul_f32 v[36:37], v[36:37], v[52:53] op_sel_hi:[1,0]
	v_pk_mul_f32 v[34:35], v[34:35], v[52:53] op_sel_hi:[1,0]
	v_pk_mul_f32 v[32:33], v[32:33], v[52:53] op_sel_hi:[1,0]
	v_pk_mul_f32 v[30:31], v[30:31], v[52:53] op_sel_hi:[1,0]
	v_pk_mul_f32 v[28:29], v[28:29], v[52:53] op_sel_hi:[1,0]
	v_pk_mul_f32 v[26:27], v[26:27], v[52:53] op_sel_hi:[1,0]
	v_pk_mul_f32 v[24:25], v[24:25], v[52:53] op_sel_hi:[1,0]
	v_pk_mul_f32 v[22:23], v[22:23], v[52:53] op_sel_hi:[1,0]
	v_pk_mul_f32 v[20:21], v[20:21], v[52:53] op_sel_hi:[1,0]
	v_pk_mul_f32 v[18:19], v[18:19], v[52:53] op_sel_hi:[1,0]
	v_pk_mul_f32 v[16:17], v[16:17], v[52:53] op_sel_hi:[1,0]
	v_pk_add_f32 v[94:95], v[94:95], v[50:51] op_sel_hi:[1,0] neg_lo:[0,1] neg_hi:[0,1]
	v_pk_add_f32 v[78:79], v[78:79], v[50:51] op_sel_hi:[1,0] neg_lo:[0,1] neg_hi:[0,1]
	v_mov_b32_e32 v49, v48
	v_mov_b32_e32 v50, v48
	v_mov_b32_e32 v51, v48
	v_mov_b32_e32 v52, v48
	v_mov_b32_e32 v53, v48
	v_mov_b32_e32 v54, v48
	v_mov_b32_e32 v55, v48
	v_mov_b32_e32 v56, v48
	v_mov_b32_e32 v57, v48
	v_mov_b32_e32 v58, v48
	v_mov_b32_e32 v59, v48
	v_mov_b32_e32 v60, v48
	v_mov_b32_e32 v61, v48
	v_mov_b32_e32 v62, v48
	v_mov_b32_e32 v63, v48

.LBB0_384:
	s_nop 7
	v_max3_f32 v154, v80, v81, v82
	v_max3_f32 v154, v154, v83, v84
	v_max3_f32 v154, v154, v85, v86
	v_max3_f32 v154, v154, v87, v88
	v_max3_f32 v154, v154, v89, v90
	v_max3_f32 v154, v154, v91, v92
	v_max3_f32 v154, v154, v93, v94
	v_max3_f32 v156, v64, v65, v66
	v_max3_f32 v156, v156, v67, v68
	v_max3_f32 v156, v156, v69, v70
	v_max3_f32 v156, v156, v71, v72
	v_max3_f32 v156, v156, v73, v74
	v_max3_f32 v156, v156, v75, v76
	v_max3_f32 v156, v156, v77, v78
	v_max3_f32 v153, v154, v156, v95
	v_max_f32_e32 v153, v153, v79
	v_mov_b32_e32 v154, v153
	s_nop 1
	v_permlane32_swap_b32_e32 v153, v154
	v_max_f32_e32 v154, v154, v154
	v_max_f32_e32 v153, v153, v153
	v_max_f32_e32 v153, v153, v154
	v_cndmask_b32_e64 v154, v227, v228, s[30:31]
	v_cmp_gt_f32_e32 vcc, v153, v154
	s_cbranch_vccz .LBB0_386
	s_nop 0
	v_cndmask_b32_e32 v50, 0, v153, vcc
	v_exp_f32_e64 v52, -v50
	v_add_f32_e32 v48, v143, v50
	v_xor_b32_e32 v48, 0x80000000, v48
	v_pk_add_f32 v[80:81], v[80:81], v[50:51] op_sel_hi:[1,0] neg_lo:[0,1] neg_hi:[0,1]
	v_mul_f32_e32 v0, v0, v52
	v_pk_add_f32 v[64:65], v[64:65], v[50:51] op_sel_hi:[1,0] neg_lo:[0,1] neg_hi:[0,1]
	v_pk_add_f32 v[82:83], v[82:83], v[50:51] op_sel_hi:[1,0] neg_lo:[0,1] neg_hi:[0,1]
	v_pk_add_f32 v[66:67], v[66:67], v[50:51] op_sel_hi:[1,0] neg_lo:[0,1] neg_hi:[0,1]
	v_pk_add_f32 v[84:85], v[84:85], v[50:51] op_sel_hi:[1,0] neg_lo:[0,1] neg_hi:[0,1]
	v_pk_add_f32 v[68:69], v[68:69], v[50:51] op_sel_hi:[1,0] neg_lo:[0,1] neg_hi:[0,1]
	v_pk_add_f32 v[86:87], v[86:87], v[50:51] op_sel_hi:[1,0] neg_lo:[0,1] neg_hi:[0,1]
	v_pk_add_f32 v[70:71], v[70:71], v[50:51] op_sel_hi:[1,0] neg_lo:[0,1] neg_hi:[0,1]
	v_pk_add_f32 v[88:89], v[88:89], v[50:51] op_sel_hi:[1,0] neg_lo:[0,1] neg_hi:[0,1]
	v_pk_add_f32 v[72:73], v[72:73], v[50:51] op_sel_hi:[1,0] neg_lo:[0,1] neg_hi:[0,1]
	v_pk_add_f32 v[90:91], v[90:91], v[50:51] op_sel_hi:[1,0] neg_lo:[0,1] neg_hi:[0,1]
	v_pk_add_f32 v[74:75], v[74:75], v[50:51] op_sel_hi:[1,0] neg_lo:[0,1] neg_hi:[0,1]
	v_pk_add_f32 v[92:93], v[92:93], v[50:51] op_sel_hi:[1,0] neg_lo:[0,1] neg_hi:[0,1]
	v_pk_add_f32 v[76:77], v[76:77], v[50:51] op_sel_hi:[1,0] neg_lo:[0,1] neg_hi:[0,1]
	v_pk_mul_f32 v[46:47], v[46:47], v[52:53] op_sel_hi:[1,0]
	v_pk_mul_f32 v[44:45], v[44:45], v[52:53] op_sel_hi:[1,0]
	v_pk_mul_f32 v[42:43], v[42:43], v[52:53] op_sel_hi:[1,0]
	v_pk_mul_f32 v[40:41], v[40:41], v[52:53] op_sel_hi:[1,0]
	v_pk_mul_f32 v[38:39], v[38:39], v[52:53] op_sel_hi:[1,0]
	v_pk_mul_f32 v[36:37], v[36:37], v[52:53] op_sel_hi:[1,0]
	v_pk_mul_f32 v[34:35], v[34:35], v[52:53] op_sel_hi:[1,0]
	v_pk_mul_f32 v[32:33], v[32:33], v[52:53] op_sel_hi:[1,0]
	v_pk_mul_f32 v[30:31], v[30:31], v[52:53] op_sel_hi:[1,0]
	v_pk_mul_f32 v[28:29], v[28:29], v[52:53] op_sel_hi:[1,0]
	v_pk_mul_f32 v[26:27], v[26:27], v[52:53] op_sel_hi:[1,0]
	v_pk_mul_f32 v[24:25], v[24:25], v[52:53] op_sel_hi:[1,0]
	v_pk_mul_f32 v[22:23], v[22:23], v[52:53] op_sel_hi:[1,0]
	v_pk_mul_f32 v[20:21], v[20:21], v[52:53] op_sel_hi:[1,0]
	v_pk_mul_f32 v[18:19], v[18:19], v[52:53] op_sel_hi:[1,0]
	v_pk_mul_f32 v[16:17], v[16:17], v[52:53] op_sel_hi:[1,0]
	v_pk_add_f32 v[94:95], v[94:95], v[50:51] op_sel_hi:[1,0] neg_lo:[0,1] neg_hi:[0,1]
	v_pk_add_f32 v[78:79], v[78:79], v[50:51] op_sel_hi:[1,0] neg_lo:[0,1] neg_hi:[0,1]
	v_mov_b32_e32 v49, v48
	v_mov_b32_e32 v50, v48
	v_mov_b32_e32 v51, v48
	v_mov_b32_e32 v52, v48
	v_mov_b32_e32 v53, v48
	v_mov_b32_e32 v54, v48
	v_mov_b32_e32 v55, v48
	v_mov_b32_e32 v56, v48
	v_mov_b32_e32 v57, v48
	v_mov_b32_e32 v58, v48
	v_mov_b32_e32 v59, v48
	v_mov_b32_e32 v60, v48
	v_mov_b32_e32 v61, v48
	v_mov_b32_e32 v62, v48
	v_mov_b32_e32 v63, v48

.LBB0_390:
	s_nop 7
	v_max3_f32 v87, v64, v65, v66
	v_max3_f32 v87, v87, v67, v68
	v_max3_f32 v87, v87, v69, v70
	v_max3_f32 v87, v87, v71, v72
	v_max3_f32 v87, v87, v73, v74
	v_max3_f32 v87, v87, v75, v76
	v_max3_f32 v87, v87, v77, v78
	v_max3_f32 v88, v48, v49, v50
	v_max3_f32 v88, v88, v51, v52
	v_max3_f32 v88, v88, v53, v54
	v_max3_f32 v88, v88, v55, v56
	v_max3_f32 v88, v88, v57, v58
	v_max3_f32 v88, v88, v59, v60
	v_max3_f32 v88, v88, v61, v62
	v_max3_f32 v86, v87, v88, v79
	v_max_f32_e32 v86, v86, v63
	v_mov_b32_e32 v87, v86
	s_nop 1
	v_permlane32_swap_b32_e32 v86, v87
	v_max_f32_e32 v87, v87, v87
	v_max_f32_e32 v86, v86, v86
	v_max_f32_e32 v86, v86, v87
	v_cndmask_b32_e64 v87, v227, v228, s[30:31]
	v_cmp_gt_f32_e32 vcc, v86, v87
	s_cbranch_vccz .LBB0_198
	s_nop 0
	v_cndmask_b32_e32 v86, 0, v86, vcc
	v_exp_f32_e64 v88, -v86
	v_pk_add_f32 v[64:65], v[64:65], v[86:87] op_sel_hi:[1,0] neg_lo:[0,1] neg_hi:[0,1]
	v_pk_add_f32 v[48:49], v[48:49], v[86:87] op_sel_hi:[1,0] neg_lo:[0,1] neg_hi:[0,1]
	v_pk_add_f32 v[66:67], v[66:67], v[86:87] op_sel_hi:[1,0] neg_lo:[0,1] neg_hi:[0,1]
	v_mul_f32_e32 v0, v0, v88
	v_pk_add_f32 v[50:51], v[50:51], v[86:87] op_sel_hi:[1,0] neg_lo:[0,1] neg_hi:[0,1]
	v_pk_add_f32 v[68:69], v[68:69], v[86:87] op_sel_hi:[1,0] neg_lo:[0,1] neg_hi:[0,1]
	v_pk_add_f32 v[52:53], v[52:53], v[86:87] op_sel_hi:[1,0] neg_lo:[0,1] neg_hi:[0,1]
	v_pk_add_f32 v[70:71], v[70:71], v[86:87] op_sel_hi:[1,0] neg_lo:[0,1] neg_hi:[0,1]
	v_pk_add_f32 v[54:55], v[54:55], v[86:87] op_sel_hi:[1,0] neg_lo:[0,1] neg_hi:[0,1]
	v_pk_add_f32 v[72:73], v[72:73], v[86:87] op_sel_hi:[1,0] neg_lo:[0,1] neg_hi:[0,1]
	v_pk_add_f32 v[56:57], v[56:57], v[86:87] op_sel_hi:[1,0] neg_lo:[0,1] neg_hi:[0,1]
	v_pk_add_f32 v[74:75], v[74:75], v[86:87] op_sel_hi:[1,0] neg_lo:[0,1] neg_hi:[0,1]
	v_pk_add_f32 v[58:59], v[58:59], v[86:87] op_sel_hi:[1,0] neg_lo:[0,1] neg_hi:[0,1]
	v_pk_add_f32 v[76:77], v[76:77], v[86:87] op_sel_hi:[1,0] neg_lo:[0,1] neg_hi:[0,1]
	v_pk_add_f32 v[60:61], v[60:61], v[86:87] op_sel_hi:[1,0] neg_lo:[0,1] neg_hi:[0,1]
	v_pk_mul_f32 v[46:47], v[46:47], v[88:89] op_sel_hi:[1,0]
	v_pk_mul_f32 v[44:45], v[44:45], v[88:89] op_sel_hi:[1,0]
	v_pk_mul_f32 v[42:43], v[42:43], v[88:89] op_sel_hi:[1,0]
	v_pk_mul_f32 v[40:41], v[40:41], v[88:89] op_sel_hi:[1,0]
	v_pk_mul_f32 v[38:39], v[38:39], v[88:89] op_sel_hi:[1,0]
	v_pk_mul_f32 v[36:37], v[36:37], v[88:89] op_sel_hi:[1,0]
	v_pk_mul_f32 v[34:35], v[34:35], v[88:89] op_sel_hi:[1,0]
	v_pk_mul_f32 v[32:33], v[32:33], v[88:89] op_sel_hi:[1,0]
	v_pk_mul_f32 v[30:31], v[30:31], v[88:89] op_sel_hi:[1,0]
	v_pk_mul_f32 v[28:29], v[28:29], v[88:89] op_sel_hi:[1,0]
	v_pk_mul_f32 v[26:27], v[26:27], v[88:89] op_sel_hi:[1,0]
	v_pk_mul_f32 v[24:25], v[24:25], v[88:89] op_sel_hi:[1,0]
	v_pk_mul_f32 v[22:23], v[22:23], v[88:89] op_sel_hi:[1,0]
	v_pk_mul_f32 v[20:21], v[20:21], v[88:89] op_sel_hi:[1,0]
	v_pk_mul_f32 v[18:19], v[18:19], v[88:89] op_sel_hi:[1,0]
	v_pk_mul_f32 v[16:17], v[16:17], v[88:89] op_sel_hi:[1,0]
	v_pk_add_f32 v[78:79], v[78:79], v[86:87] op_sel_hi:[1,0] neg_lo:[0,1] neg_hi:[0,1]
	v_pk_add_f32 v[62:63], v[62:63], v[86:87] op_sel_hi:[1,0] neg_lo:[0,1] neg_hi:[0,1]
	s_branch .LBB0_198
